# sample items rebalanced between GDN-scan and GLA-scan workgroups (one GDN sample item moved from each GDN-scan workgroup to a GLA-scan workgroup)
# speedup vs baseline: 1.1321x; 1.0078x over previous
.LBB0_1009:
	s_add_i32 s84, s84, s48
	v_readlane_b32 s32, v246, 0
	s_nop 1
	s_sub_i32 s100, s84, s32
	s_cmp_lt_u32 s32, 0x80
	s_cbranch_scc0 .Lsm_hi
	s_cmp_eq_u32 s100, 0x300
	s_cbranch_scc0 .Lsm_done
	s_add_i32 s84, s84, 0x100
	s_branch .Lsm_done
.Lsm_hi:
	s_cmp_eq_u32 s100, 0x300
	s_cbranch_scc0 .Lsm_hi2
	s_sub_i32 s84, s84, 0x80
	s_branch .Lsm_done
.Lsm_hi2:
	s_cmp_eq_u32 s100, 0x380
	s_cbranch_scc0 .Lsm_done
	s_sub_i32 s84, s84, 0x80
.Lsm_done:
	s_cmpk_lt_i32 s84, 0x600
	s_cbranch_scc0 .LBB0_1080
.LBB0_1010:
	s_cmpk_gt_i32 s84, 0x3ff
	s_mov_b64 s[0:1], -1
	s_cbranch_scc1 .LBB0_1012
	s_and_b64 vcc, exec, s[0:1]
	s_cbranch_vccz .LBB0_1009
	s_branch .LBB0_1050
